# attention loop head aligned to 64 bytes (was at 4 mod 8); otherwise identical to the scalar-add version
# baseline (speedup 1.0000x reference)
; DI void attn_tile8(const Params& p, int bh, int qt, char* smem) {
;     ...
;   bf16x8 qf[6];
;   {
;     const u16* qp = p.Q + qrow * 768 + hh * 96 + lh * 8;
; #pragma unroll
;     for (int s = 0; s < 6; ++s) qf[s] = *(const bf16x8*)(qp + 16 * s);
;   }
;   u32x4 rk[3], rv[2];
;   auto load_tiles = [&](int kt) {
; #pragma unroll
;     for (int i = 0; i < 3; ++i) {
;       const int idx = tid + 512 * i, key = idx / 12, ch = idx % 12;
;       const size_t kr = rowbase + kt * 128 + key;
;       rk[i] = (ch < 8) ? *(const u32x4*)(p.Kn + kr * 512 + hh * 64 + ch * 8) : *(const u32x4*)(p.KR + kr * 32 + (ch - 8) * 8);
;     }
; #pragma unroll
;     for (int i = 0; i < 2; ++i) {
;       const int idx = tid + 512 * i, vd = idx >> 4, ch = idx & 15;
;       rv[i] = *(const u32x4*)(p.Vt + ((size_t)bh * 64 + vd) * TPB + kt * 128 + ch * 8);
;     }
;   };
.LBB1_1167:
	s_andn2_saveexec_b64 s[16:17], s[16:17]
	s_cbranch_execz .LBB1_1140
	v_lshlrev_b32_e32 v2, 8, v33
	v_mov_b32_e32 v6, v192
	v_and_b32_e32 v2, 0xf00, v2
	v_ashrrev_i32_e32 v26, 7, v33
	v_add_u32_e32 v194, 0x100, v2
	s_movk_i32 s4, 0x1100
	v_ashrrev_i32_e32 v4, 1, v6
	v_and_b32_e32 v27, 31, v6
	v_mad_i64_i32 v[2:3], s[2:3], v26, s4, v[194:195]
	v_and_b32_e32 v4, 0xffffffe0, v4
	v_ashrrev_i32_e32 v0, 4, v33
	v_ashrrev_i32_e32 v5, 31, v4
	v_or_b32_e32 v2, v2, v27
	v_and_b32_e32 v1, 7, v0
	v_lshl_add_u64 v[140:141], v[2:3], 0, v[4:5]
	v_mov_b64_e32 v[2:3], s[66:67]
	s_movk_i32 s5, 0x600
	v_mad_u64_u32 v[2:3], s[2:3], v140, s5, v[2:3]
	v_mul_u32_u24_e32 v4, 0x60, v1
	v_bfe_u32 v170, v6, 5, 1
	v_mad_i32_i24 v3, v141, s5, v3
	v_lshlrev_b32_e32 v194, 1, v4
	v_lshl_add_u64 v[2:3], v[2:3], 0, v[194:195]
	v_lshlrev_b32_e32 v194, 4, v170
	v_lshl_add_u64 v[2:3], v[2:3], 0, v[194:195]
	global_load_dwordx4 v[96:99], v[2:3], off
	global_load_dwordx4 v[100:103], v[2:3], off offset:32
	global_load_dwordx4 v[104:107], v[2:3], off offset:64
	global_load_dwordx4 v[108:111], v[2:3], off offset:96
	global_load_dwordx4 v[112:115], v[2:3], off offset:128
	global_load_dwordx4 v[116:119], v[2:3], off offset:160
	s_mov_b32 s2, 0x2aaaaaab
	v_mul_hi_i32 v2, v6, s2
	v_lshrrev_b32_e32 v3, 31, v2
	v_ashrrev_i32_e32 v2, 1, v2
	v_add_u32_e32 v2, v2, v3
	v_mul_lo_u32 v3, v2, 12
	v_sub_u32_e32 v4, v6, v3
	v_ashrrev_i32_e32 v3, 31, v2
	v_mad_i64_i32 v[10:11], s[2:3], v26, s4, v[2:3]
	s_movk_i32 s18, 0x1100
	v_cmp_gt_i32_e64 s[2:3], 8, v4
	v_cmp_lt_i32_e32 vcc, 7, v4
	v_lshlrev_b32_e32 v144, 4, v4
	s_and_saveexec_b64 s[4:5], vcc
	s_xor_b64 s[4:5], exec, s[4:5]
	v_lshlrev_b64 v[8:9], 6, v[10:11]
	v_lshl_add_u64 v[8:9], s[72:73], 0, v[8:9]
	v_mov_b32_e32 v145, v195
	s_movk_i32 s6, 0xff80
	v_lshl_add_u64 v[8:9], v[8:9], 0, v[144:145]
	s_mov_b32 s7, -1
	v_lshl_add_u64 v[8:9], v[8:9], 0, s[6:7]
	s_or_saveexec_b64 s[4:5], s[4:5]
	v_lshlrev_b32_e32 v4, 3, v4
	v_lshlrev_b32_e32 v18, 7, v1
	v_ashrrev_i32_e32 v7, 31, v4
	s_xor_b64 exec, exec, s[4:5]
	v_lshlrev_b64 v[8:9], 10, v[10:11]
	v_lshl_add_u64 v[8:9], s[68:69], 0, v[8:9]
	v_mov_b32_e32 v19, v195
	v_lshl_add_u64 v[8:9], v[8:9], 0, v[18:19]
	v_mov_b32_e32 v5, v7
	v_lshl_add_u64 v[8:9], v[4:5], 1, v[8:9]
	s_or_b64 exec, exec, s[4:5]
	global_load_dwordx4 v[120:123], v[8:9], off
	v_mad_i64_i32 v[16:17], s[4:5], v26, s18, 0
	v_add_u32_e32 v5, 0x200, v6
	s_mov_b32 s4, 0x2aaaaaab
	v_mul_hi_i32 v8, v5, s4
	v_lshrrev_b32_e32 v9, 31, v8
	v_ashrrev_i32_e32 v8, 1, v8
	v_add_u32_e32 v8, v8, v9
	v_mul_lo_u32 v9, v8, 12
	v_sub_u32_e32 v10, v5, v9
	v_ashrrev_i32_e32 v9, 31, v8
	v_lshl_add_u64 v[20:21], v[16:17], 0, v[8:9]
	v_cmp_gt_i32_e64 s[4:5], 8, v10
	v_cmp_lt_i32_e32 vcc, 7, v10
	v_lshlrev_b32_e32 v146, 4, v10
	s_and_saveexec_b64 s[6:7], vcc
	s_xor_b64 s[6:7], exec, s[6:7]
	v_lshlrev_b64 v[12:13], 6, v[20:21]
	v_lshl_add_u64 v[12:13], s[72:73], 0, v[12:13]
	v_mov_b32_e32 v147, v195
	s_movk_i32 s18, 0xff80
	v_lshl_add_u64 v[12:13], v[12:13], 0, v[146:147]
	s_mov_b32 s19, -1
	v_lshl_add_u64 v[14:15], v[12:13], 0, s[18:19]
	s_or_saveexec_b64 s[6:7], s[6:7]
	v_lshlrev_b32_e32 v10, 3, v10
	v_ashrrev_i32_e32 v13, 31, v10
	s_xor_b64 exec, exec, s[6:7]
	v_lshlrev_b64 v[14:15], 10, v[20:21]
	v_lshl_add_u64 v[14:15], s[68:69], 0, v[14:15]
	v_mov_b32_e32 v19, v195
	v_lshl_add_u64 v[14:15], v[14:15], 0, v[18:19]
	v_mov_b32_e32 v11, v13
	v_lshl_add_u64 v[14:15], v[10:11], 1, v[14:15]
	s_or_b64 exec, exec, s[6:7]
	global_load_dwordx4 v[124:127], v[14:15], off
	v_add_u32_e32 v11, 0x400, v6
	s_mov_b32 s6, 0x2aaaaaab
	v_mul_hi_i32 v12, v11, s6
	v_lshrrev_b32_e32 v14, 31, v12
	v_ashrrev_i32_e32 v12, 1, v12
	v_add_u32_e32 v14, v12, v14
	v_mul_lo_u32 v12, v14, 12
	v_sub_u32_e32 v11, v11, v12
	v_ashrrev_i32_e32 v15, 31, v14
	v_lshl_add_u64 v[24:25], v[16:17], 0, v[14:15]
	v_cmp_gt_i32_e64 s[6:7], 8, v11
	v_cmp_lt_i32_e32 vcc, 7, v11
	v_lshlrev_b32_e32 v16, 3, v11
	v_lshlrev_b32_e32 v148, 4, v11
	v_lshlrev_b32_e32 v142, 6, v1
	s_and_saveexec_b64 s[18:19], vcc
	s_xor_b64 s[18:19], exec, s[18:19]
	v_lshlrev_b64 v[18:19], 6, v[24:25]
	v_lshl_add_u64 v[18:19], s[72:73], 0, v[18:19]
	v_mov_b32_e32 v149, v195
	s_movk_i32 s20, 0xff80
	v_lshl_add_u64 v[18:19], v[18:19], 0, v[148:149]
	s_mov_b32 s21, -1
	v_mov_b32_e32 v17, v195
	v_lshl_add_u64 v[22:23], v[18:19], 0, s[20:21]
	v_mov_b32_e32 v143, v195
	s_or_saveexec_b64 s[18:19], s[18:19]
	v_mov_b64_e32 v[20:21], v[16:17]
	s_xor_b64 exec, exec, s[18:19]
	v_lshlrev_b64 v[20:21], 10, v[24:25]
	v_lshl_add_u64 v[20:21], s[68:69], 0, v[20:21]
	v_mov_b32_e32 v19, v195
	v_lshl_add_u64 v[18:19], v[20:21], 0, v[18:19]
	v_ashrrev_i32_e32 v17, 31, v16
	v_mov_b32_e32 v143, v195
	v_lshl_add_u64 v[22:23], v[16:17], 1, v[18:19]
	v_mov_b32_e32 v20, v16
	v_mov_b32_e32 v21, v195
	s_or_b64 exec, exec, s[18:19]
	v_ashrrev_i32_e32 v18, 4, v6
	v_ashrrev_i32_e32 v1, 31, v0
	global_load_dwordx4 v[128:131], v[22:23], off
	v_lshlrev_b64 v[22:23], 6, v[0:1]
	v_ashrrev_i32_e32 v19, 31, v18
	v_lshl_add_u64 v[24:25], v[22:23], 0, v[18:19]
	v_mov_b64_e32 v[28:29], s[70:71]
	s_movk_i32 s20, 0x2200
	v_mad_u64_u32 v[30:31], s[18:19], v24, s20, v[28:29]
	v_lshlrev_b32_e32 v1, 4, v6
	v_mad_i32_i24 v31, v25, s20, v31
	v_and_b32_e32 v150, 0xf0, v1
	v_mov_b32_e32 v151, v195
	v_lshl_add_u64 v[24:25], v[30:31], 0, v[150:151]
	v_ashrrev_i32_e32 v30, 4, v5
	v_ashrrev_i32_e32 v31, 31, v30
	v_lshl_add_u64 v[22:23], v[22:23], 0, v[30:31]
	v_mad_u64_u32 v[28:29], s[18:19], v22, s20, v[28:29]
	v_mad_i32_i24 v29, v23, s20, v29
	v_lshl_add_u64 v[22:23], v[28:29], 0, v[150:151]
	global_load_dwordx4 v[132:135], v[24:25], off
	global_load_dwordx4 v[136:139], v[22:23], off
	s_movk_i32 s18, 0xd0
	v_mul_lo_u32 v147, v2, s18
	v_mul_lo_u32 v149, v8, s18
	v_mul_lo_u32 v151, v14, s18
	v_and_b32_e32 v19, 64, v211
	v_lshlrev_b64 v[22:23], 10, v[14:15]
	s_movk_i32 s18, 0x108
	s_mov_b32 s23, 0x440000
	v_xor_b32_e32 v1, 32, v211
	v_mul_lo_u32 v173, v18, s18
	v_mul_lo_u32 v174, v30, s18
	s_waitcnt lgkmcnt(0)
; #define MFMA32(a, b, c) __builtin_amdgcn_mfma_f32_32x32x16_bf16((a), (b), (c), 0, 0, 0)
; DI void attn_tile8(const Params& p, int bh, int qt, char* smem) {
;     ...
;   auto store_tiles = [&](int st) {
;     char* Ks = smem + st * STAGE;
;     char* Vs = Ks + VOFF;
; #pragma unroll
;     for (int i = 0; i < 3; ++i) {
;       const int idx = tid + 512 * i, key = idx / 12, ch = idx % 12;
;       *(u32x4*)(Ks + key * 208 + ch * 16) = rk[i];
;     }
; #pragma unroll
;     for (int i = 0; i < 2; ++i) {
;       const int idx = tid + 512 * i, vd = idx >> 4, ch = idx & 15;
;       uint2* d = (uint2*)(Vs + vd * VROW + ch * 16);
;       d[0] = make_uint2(rv[i].x, rv[i].y);
;       d[1] = make_uint2(rv[i].z, rv[i].w);
;     }
;   };
;   f32x16 O[2];
; #pragma unroll
;   for (int i = 0; i < 16; ++i) { O[0][i] = 0.f; O[1][i] = 0.f; }
;   float m = -1e30f, lsum = 0.f;
;   load_tiles(0);
;   store_tiles(0);
;   __syncthreads();
;     ...
;     {
;       bf16x8 kf[2][4];
; #pragma unroll
;       for (int kb = 0; kb < 4; ++kb) kf[0][kb] = *(const bf16x8*)(Ks + (kb * 32 + lr) * 208 + lh * 16);
; #pragma unroll
;       for (int s = 0; s < 6; ++s) {
;         if (s < 5) {
; #pragma unroll
;           for (int kb = 0; kb < 4; ++kb) kf[(s + 1) & 1][kb] = *(const bf16x8*)(Ks + (kb * 32 + lr) * 208 + (s + 1) * 32 + lh * 16);
;         }
;         __builtin_amdgcn_sched_barrier(0);
;         __builtin_amdgcn_s_setprio(1);
; #pragma unroll
;         for (int kb = 0; kb < 4; ++kb) st[kb] = MFMA32(kf[s & 1][kb], qf[s], st[kb]);
;         __builtin_amdgcn_s_setprio(0);
;         __builtin_amdgcn_sched_barrier(0);
;       }
;     }
;     float mx = st[0][0];
; #pragma unroll
;     for (int kb = 0; kb < 4; ++kb)
; #pragma unroll
;       for (int i = 0; i < 16; ++i) mx = fmaxf(mx, st[kb][i]);
;     mx = fmaxf(mx, __shfl_xor(mx, 32));
;     const float mn = fmaxf(m, mx);
;     const float alpha = __builtin_amdgcn_exp2f(m - mn);
;     m = mn;
	v_add_u32_e32 v34, 64, v19
	v_mad_i64_i32 v[18:19], s[18:19], v18, s20, 0
	v_mad_i64_i32 v[30:31], s[18:19], v30, s20, 0
	v_mad_i64_i32 v[22:23], s[18:19], v26, s23, v[22:23]
	v_mul_u32_u24_e32 v171, 0xd0, v27
	v_mul_u32_u24_e32 v172, 0x108, v27
	v_lshlrev_b64 v[14:15], 6, v[14:15]
	v_mov_b64_e32 v[24:25], s[72:73]
	v_lshlrev_b64 v[28:29], 10, v[8:9]
	v_add3_u32 v27, 0, v147, v144
	s_mov_b32 s18, 0x44000
	v_cmp_lt_i32_e32 vcc, v1, v34
	s_mov_b32 s20, 0x88000
	v_add3_u32 v32, 0, v149, v146
	v_lshl_add_u64 v[14:15], v[20:21], 1, v[14:15]
	v_mad_i64_i32 v[152:153], s[18:19], v26, s18, v[24:25]
	v_mad_i64_i32 v[20:21], s[18:19], v26, s23, v[28:29]
	s_waitcnt vmcnt(4)
	ds_write_b128 v27, v[120:123]
	s_waitcnt vmcnt(3)
	ds_write_b128 v32, v[124:127]
	v_cndmask_b32_e32 v27, v211, v1, vcc
	v_mad_i64_i32 v[18:19], s[18:19], v0, s20, v[18:19]
	v_mad_i64_i32 v[0:1], s[18:19], v0, s20, v[30:31]
	v_add_u32_e32 v24, 0, v173
	v_add_u32_e32 v25, 0, v174
	s_mov_b64 s[34:35], 0x1f80
	s_movk_i32 s18, 0x6800
	v_lshl_add_u64 v[154:155], v[14:15], 0, s[34:35]
	v_add3_u32 v14, v24, v150, s18
	v_add3_u32 v15, v25, v150, s18
	v_readlane_b32 s18, v235, 44
	v_or_b32_e32 v0, v0, v150
	v_readlane_b32 s19, v235, 45
	v_mov_b32_e32 v11, v195
	v_mov_b32_e32 v6, v4
	v_lshl_add_u64 v[162:163], s[18:19], 0, v[0:1]
	v_lshlrev_b64 v[0:1], 6, v[8:9]
	v_lshl_add_u64 v[0:1], v[10:11], 1, v[0:1]
	v_or_b32_e32 v18, v18, v150
	v_lshl_add_u64 v[164:165], v[0:1], 0, s[34:35]
	v_lshlrev_b64 v[0:1], 10, v[2:3]
	v_readlane_b32 s20, v235, 46
	v_lshl_add_u64 v[160:161], s[18:19], 0, v[18:19]
	v_mad_i64_i32 v[0:1], s[18:19], v26, s23, v[0:1]
	v_lshl_add_u64 v[6:7], v[142:143], 0, v[6:7]
	v_mov_b32_e32 v12, v10
	v_readlane_b32 s21, v235, 47
	v_lshl_add_u64 v[0:1], v[6:7], 1, v[0:1]
	v_mov_b32_e32 v5, v195
	v_lshl_add_u64 v[16:17], v[16:17], 0, v[142:143]
	v_lshl_add_u64 v[12:13], v[142:143], 0, v[12:13]
	v_lshl_add_u64 v[166:167], s[20:21], 0, v[0:1]
	v_lshlrev_b64 v[0:1], 6, v[2:3]
	v_add3_u32 v33, 0, v151, v148
	v_lshl_add_u64 v[16:17], v[16:17], 1, v[22:23]
	v_lshl_add_u64 v[12:13], v[12:13], 1, v[20:21]
	v_lshl_add_u64 v[0:1], v[4:5], 1, v[0:1]
	v_mov_b32_e32 v176, 0
	v_lshlrev_b32_e32 v145, 3, v170
	s_mov_b32 s31, 0
	v_lshlrev_b32_e32 v175, 2, v27
	v_lshl_add_u64 v[156:157], s[20:21], 0, v[16:17]
	v_lshl_add_u64 v[158:159], s[20:21], 0, v[12:13]
	s_waitcnt vmcnt(2)
	ds_write_b128 v33, v[128:131]
	s_waitcnt vmcnt(1)
	ds_write2_b64 v14, v[132:133], v[134:135] offset1:1
	s_waitcnt vmcnt(0)
	ds_write2_b64 v15, v[136:137], v[138:139] offset1:1
	v_lshl_add_u64 v[168:169], v[0:1], 0, s[34:35]
	v_mov_b32_e32 v178, 0xf149f2ca
	s_mov_b64 s[18:19], 0
	v_mov_b32_e32 v16, 0
	v_mov_b32_e32 v17, v176
	v_mov_b32_e32 v18, v176
	v_mov_b32_e32 v19, v176
	v_mov_b32_e32 v20, v176
	v_mov_b32_e32 v21, v176
	v_mov_b32_e32 v22, v176
	v_mov_b32_e32 v23, v176
	v_mov_b32_e32 v24, v176
	v_mov_b32_e32 v25, v176
	v_mov_b32_e32 v26, v176
	v_mov_b32_e32 v27, v176
	v_mov_b32_e32 v28, v176
	v_mov_b32_e32 v29, v176
	v_mov_b32_e32 v30, v176
	v_mov_b32_e32 v31, v176
	v_mov_b32_e32 v0, 0
	v_mov_b32_e32 v1, v176
	v_mov_b32_e32 v2, v176
	v_mov_b32_e32 v3, v176
	v_mov_b32_e32 v4, v176
	v_mov_b32_e32 v5, v176
	v_mov_b32_e32 v6, v176
	v_mov_b32_e32 v7, v176
	v_mov_b32_e32 v8, v176
	v_mov_b32_e32 v9, v176
	v_mov_b32_e32 v10, v176
	v_mov_b32_e32 v11, v176
	v_mov_b32_e32 v12, v176
	v_mov_b32_e32 v13, v176
	v_mov_b32_e32 v14, v176
	v_mov_b32_e32 v15, v176
	s_waitcnt lgkmcnt(0)
	s_barrier
	v_add_u32_e32 v177, v194, v171
	ds_read_b128 v[180:183], v177 offset:0
	ds_read_b128 v[184:187], v177 offset:32
	ds_read_b128 v[188:191], v177 offset:64
	ds_read_b128 v[200:203], v177 offset:96
	v_sub_u32_e32 v213, 1, v170
	v_mul_u32_u24_e32 v214, 0x3f80, v213
	v_mov_b32_e32 v215, 0
	v_mov_b32_e32 v216, 0
	v_mov_b32_e32 v217, 0
	v_mov_b32_e32 v219, 0
	v_mov_b32_e32 v220, 0
	v_mov_b32_e32 v221, 0
	s_waitcnt lgkmcnt(3)
	v_mfma_f32_32x32x16_bf16 v[80:95], v[180:183], v[96:99], 0
	ds_read_b128 v[180:183], v177 offset:128
	s_waitcnt lgkmcnt(3)
	v_mfma_f32_32x32x16_bf16 v[80:95], v[184:187], v[100:103], v[80:95]
	ds_read_b128 v[184:187], v177 offset:160
	s_waitcnt lgkmcnt(3)
	v_mfma_f32_32x32x16_bf16 v[80:95], v[188:191], v[104:107], v[80:95]
	s_waitcnt lgkmcnt(2)
	v_mfma_f32_32x32x16_bf16 v[80:95], v[200:203], v[108:111], v[80:95]
	s_waitcnt lgkmcnt(1)
	v_mfma_f32_32x32x16_bf16 v[80:95], v[180:183], v[112:115], v[80:95]
	s_waitcnt lgkmcnt(0)
	v_mfma_f32_32x32x16_bf16 v[80:95], v[184:187], v[116:119], v[80:95]
	s_nop 11
	v_max_f32_e32 v232, v80, v81
	v_max3_f32 v232, v232, v82, v83
	v_max3_f32 v232, v232, v84, v85
	v_max3_f32 v232, v232, v86, v87
	v_max3_f32 v232, v232, v88, v89
	v_max3_f32 v232, v232, v90, v91
	v_max3_f32 v232, v232, v92, v93
	v_max3_f32 v232, v232, v94, v95
	ds_bpermute_b32 v233, v175, v232
	s_waitcnt lgkmcnt(0)
	v_max_f32_e32 v213, v232, v233
	v_cvt_pk_bf16_f32 v213, v213, 0
	v_xor_b32_e32 v218, 0x8000, v213
	v_lshlrev_b32_e32 v178, 16, v213
	v_mov_b32_e32 v232, 0
	v_mov_b32_e32 v233, 0
	v_mov_b32_e32 v238, 0
	v_mov_b32_e32 v239, 0
	.p2align 6
